# adds: first K/V tile loads before Q staging, softmax alpha-skip and shorter row-sum tail, scalar andn2 instead of cndmask+cmp flag conversions in the attention tile loop
# speedup vs baseline: 1.0110x; 1.0091x over previous
; template <int NS, int SI>
; __device__ __forceinline__ void attn_stream(const unsigned char* kbase, const unsigned char* vbase, const unsigned char* q_rd, bool mask_tail, int last_valid, int hh, float sc,
;                                             f32x16 (&O)[4], float& mrun, float& lrun) {
;     ...
;     for (int k2 = 0; k2 < 8 / NS; ++k2) {
;         const int ks = SI * (8 / NS) + k2;
;         if (k2 == 2 || k2 == 4 || k2 == 6) __builtin_amdgcn_sched_barrier(0);
;         const bf16x8 qf = *(const bf16x8*)(q_rd + ks * 32);
;         const bf16x8 k0 = *(const bf16x8*)(kbase + ks * 32);
;         const bf16x8 k1 = *(const bf16x8*)(kbase + 32 * A_KRS + ks * 32);
;         S0 = __builtin_amdgcn_mfma_f32_32x32x16_bf16(k0, qf, S0, 0, 0, 0);
;         S1 = __builtin_amdgcn_mfma_f32_32x32x16_bf16(k1, qf, S1, 0, 0, 0);
;     }
;     __builtin_amdgcn_sched_barrier(0);
;     if (mask_tail) {
;         const int thr = last_valid - 4 * hh;
; #pragma unroll
;         for (int r = 0; r < 16; ++r) { if ((r & 3) + 8 * (r >> 2) >= thr) S0[r] = -1e30f; if (32 + (r & 3) + 8 * (r >> 2) >= thr) S1[r] = -1e30f; }
; template <int NS>
; __device__ __forceinline__ void attn_unit(const AUnit& u, unsigned char* lds, const bf16_t* __restrict__ GT, bf16_t* BRc, float sc, float lam, const float* __restrict__ subln) {
;     ...
;     for (int t = 0; t < u.ntiles; ++t) {
;         const int cur = t & 1;
;         const bool more = t + 1 < u.ntiles;
;         const bool work = active && t < limit;
;         const unsigned char* kbase = lds + cur * A_BUF + k_rd;
;         const unsigned char* vbase = lds + cur * A_BUF + v_rd;
;         const bool mask_tail = (t == u.ntiles - 1) && (u.last_valid < 64);
;         unsigned char* nb = lds + (cur ^ 1) * A_BUF;
;         if (NS == 2) {
;             if (more) attn_load1(u.kb, u.ld, t + 1, rk);
;             if (work) attn_stream<NS, 0>(kbase, vbase, q_rd, mask_tail, u.last_valid, hh, sc, O0, m0, l0r);
;             if (more) { attn_store1(nb, A_KRS, rk); attn_load1(u.vb, u.ld, t + 1, rk); }
;             if (work) attn_stream<NS, 1>(kbase, vbase, q_rd, mask_tail, u.last_valid, hh, sc, O1, m1, l1r);
.LBB0_1162:
	s_and_b32 s79, s42, 1
	v_cmp_lt_i32_e32 vcc, s42, v193
	s_mul_i32 s43, s79, 0x9400
	s_and_b64 s[62:63], s[6:7], vcc
	s_add_i32 s43, s43, 0
	s_cmp_eq_u32 s61, s42
	v_add_u32_e32 v128, s43, v210
	v_add3_u32 v225, s43, v218, v219
	s_cselect_b64 s[42:43], -1, 0
	s_and_b64 s[42:43], s[4:5], s[42:43]
	v_add_u32_e32 v230, v128, v176
	s_andn2_b64 s[42:43], exec, s[42:43]
	s_and_saveexec_b64 s[44:45], s[62:63]
	s_cbranch_execz .LBB0_1168
	ds_read_b128 v[128:131], v230
	ds_read_b128 v[144:147], v222
	ds_read_b128 v[232:235], v230 offset:32
	ds_read_b128 v[236:239], v222 offset:32
	ds_read_b128 v[148:151], v230 offset:8704
	ds_read_b128 v[240:243], v230 offset:8736
	s_waitcnt lgkmcnt(4)
	v_mfma_f32_32x32x16_bf16 v[128:143], v[128:131], v[144:147], 0
	s_waitcnt lgkmcnt(1)
	v_mfma_f32_32x32x16_bf16 v[144:159], v[148:151], v[144:147], 0
	v_mfma_f32_32x32x16_bf16 v[128:143], v[232:235], v[236:239], v[128:143]
	s_waitcnt lgkmcnt(0)
	v_mfma_f32_32x32x16_bf16 v[144:159], v[240:243], v[236:239], v[144:159]
	ds_read_b128 v[232:235], v230 offset:64
	ds_read_b128 v[236:239], v222 offset:64
	ds_read_b128 v[240:243], v230 offset:96
	ds_read_b128 v[244:247], v222 offset:96
	s_waitcnt lgkmcnt(2)
	v_mfma_f32_32x32x16_bf16 v[128:143], v[232:235], v[236:239], v[128:143]
	ds_read_b128 v[232:235], v230 offset:8768
	ds_read_b128 v[248:251], v230 offset:8800
	s_waitcnt lgkmcnt(1)
	v_mfma_f32_32x32x16_bf16 v[144:159], v[232:235], v[236:239], v[144:159]
	v_mfma_f32_32x32x16_bf16 v[128:143], v[240:243], v[244:247], v[128:143]
	s_waitcnt lgkmcnt(0)
	v_mfma_f32_32x32x16_bf16 v[144:159], v[248:251], v[244:247], v[144:159]
	s_and_b64 vcc, exec, s[42:43]
	s_cbranch_vccnz .LBB0_1165
	s_or_b64 vcc, s[40:41], s[38:39]
	s_nop 8
	v_cndmask_b32_e32 v158, v223, v158, vcc
	s_or_b64 vcc, vcc, s[36:37]
	v_cndmask_b32_e32 v157, v223, v157, vcc
	s_or_b64 vcc, vcc, s[34:35]
	v_cndmask_b32_e32 v156, v223, v156, vcc
	s_or_b64 vcc, vcc, s[30:31]
	v_cndmask_b32_e32 v155, v223, v155, vcc
	s_or_b64 vcc, vcc, s[28:29]
	v_cndmask_b32_e32 v154, v223, v154, vcc
	s_or_b64 vcc, vcc, s[26:27]
	v_cndmask_b32_e32 v153, v223, v153, vcc
	s_or_b64 vcc, vcc, s[24:25]
	v_cndmask_b32_e32 v152, v223, v152, vcc
	s_or_b64 vcc, vcc, s[22:23]
	v_cndmask_b32_e32 v151, v223, v151, vcc
	s_or_b64 vcc, vcc, s[20:21]
	v_cndmask_b32_e32 v150, v223, v150, vcc
	s_or_b64 vcc, vcc, s[18:19]
	v_cndmask_b32_e32 v149, v223, v149, vcc
	s_or_b64 vcc, vcc, s[16:17]
	v_cndmask_b32_e32 v148, v223, v148, vcc
	s_or_b64 vcc, vcc, s[14:15]
	v_cndmask_b32_e32 v147, v223, v147, vcc
	s_or_b64 vcc, vcc, s[12:13]
	v_cndmask_b32_e32 v146, v223, v146, vcc
	s_or_b64 vcc, vcc, s[10:11]
	v_cndmask_b32_e32 v145, v223, v145, vcc
	s_or_b64 vcc, vcc, s[8:9]
	v_cndmask_b32_e64 v159, v223, v159, s[40:41]
	v_cndmask_b32_e32 v144, v223, v144, vcc

; template <int NS>
; __device__ __forceinline__ void attn_unit(const AUnit& u, unsigned char* lds, const bf16_t* __restrict__ GT, bf16_t* BRc, float sc, float lam, const float* __restrict__ subln) {
;     ...
;         unsigned char* nb = lds + (cur ^ 1) * A_BUF;
;         if (NS == 2) {
;             if (more) attn_load1(u.kb, u.ld, t + 1, rk);
;             if (work) attn_stream<NS, 0>(kbase, vbase, q_rd, mask_tail, u.last_valid, hh, sc, O0, m0, l0r);
;             if (more) { attn_store1(nb, A_KRS, rk); attn_load1(u.vb, u.ld, t + 1, rk); }
.LBB0_1168:
	s_or_b64 exec, exec, s[44:45]
	s_xor_b32 s44, s79, 1
	s_mul_i32 s44, s44, 0x9400
	s_add_i32 s79, s44, 0
	s_andn2_b64 s[44:45], exec, s[64:65]
	s_andn2_b64 vcc, exec, s[64:65]
	v_add_u32_e32 v231, s79, v211
	s_cbranch_vccz .LBB0_1174
	s_and_saveexec_b64 s[64:65], s[62:63]
	s_cbranch_execnz .LBB0_1175
